# phase 12: workgroups 128..255 convert ffn_w_out before their five ffn_in tiles instead of after
# speedup vs baseline: 1.0204x; 1.0025x over previous
.LBB0_1439:
	s_cmp_lt_i32 s68, 13
	s_cselect_b64 s[6:7], -1, 0
	s_and_b64 s[6:7], s[6:7], s[4:5]
	s_andn2_b64 vcc, exec, s[6:7]
	s_cbranch_vccnz .LBB0_1459
	v_lshrrev_b32_e32 v146, 1, v1
	v_lshlrev_b32_e32 v147, 2, v1
	s_cmpk_lg_i32 s70, 0x100
	s_cselect_b64 s[4:5], -1, 0
	s_add_i32 s8, s2, 0xfffffed0
	s_cmp_lt_u32 s8, 0xffffff50
	s_cselect_b64 s[8:9], -1, 0
	s_or_b64 s[4:5], s[8:9], s[4:5]
	s_and_b64 vcc, exec, s[4:5]
	s_cbranch_vccnz .Lp12_noconv
	s_load_dwordx2 s[4:5], s[0:1], 0xd8
	v_and_b32_e32 v2, 0xfc, v147
	v_lshlrev_b32_e32 v2, 2, v2
	v_mov_b32_e32 v3, 0
	v_lshrrev_b32_e32 v8, 6, v1
	s_waitcnt lgkmcnt(0)
	v_lshl_add_u64 v[4:5], s[4:5], 0, v[2:3]
	v_add_u32_e32 v6, 0, v2
	v_lshlrev_b32_e32 v2, 5, v1
	s_add_u32 s8, s66, 0xe800000
	v_mul_u32_u24_e32 v7, 0x404, v8
	v_and_b32_e32 v2, 32, v2
	s_addc_u32 s9, s67, 0
	v_lshl_add_u32 v24, v146, 2, 0
	v_mul_u32_u24_e32 v25, 0x404, v2
	s_lshl_b32 s4, s2, 8
	v_add_u32_e32 v9, v6, v7
	s_add_i32 s10, s2, 0xffffff00
	s_add_i32 s11, s4, 0xffff8000
	s_mov_b32 s12, 0x8000
	s_mov_b32 s13, 0x18000
	s_mov_b32 s14, 0x28000
	s_mov_b32 s15, 0x38000
	v_add_u32_e32 v10, 0x2020, v9
	v_add_u32_e32 v11, 0x2028, v9
	v_add_u32_e32 v12, 0x4040, v9
	v_add_u32_e32 v13, 0x4048, v9
	v_add_u32_e32 v14, 0x6060, v9
	v_add_u32_e32 v15, 0x6068, v9
	v_add_u32_e32 v16, 0x8080, v9
	v_add_u32_e32 v17, 0x8088, v9
	v_add_u32_e32 v18, 0xa0a0, v9
	v_add_u32_e32 v19, 0xa0a8, v9
	v_add_u32_e32 v20, 0xc0c0, v9
	v_add_u32_e32 v21, 0xc0c8, v9
	v_add_u32_e32 v22, 0xe0e0, v9
	v_add_u32_e32 v23, 0xe0e8, v9
	s_movk_i32 s16, 0x1600
	v_mov_b64_e32 v[6:7], s[8:9]
	v_lshlrev_b32_e32 v2, 1, v2
	v_add_u32_e32 v24, v24, v25

.Lp12_noconv:
	s_cmpk_gt_i32 s2, 0x57f
	v_readfirstlane_b32 s5, v1
	s_cbranch_scc1 .LBB0_1456
	v_lshrrev_b32_e32 v4, 5, v1
	v_and_b32_e32 v13, 24, v146
	v_and_b32_e32 v4, 4, v4
	v_bfe_u32 v5, v1, 2, 2
	s_add_u32 s33, s66, 0x1c00000
	v_lshlrev_b32_e32 v2, 4, v1
	v_and_b32_e32 v3, 32, v1
	v_bfe_u32 v12, v1, 2, 4
	v_or3_b32 v4, v4, v5, v13
	v_lshrrev_b32_e32 v5, 3, v1
	s_movk_i32 s4, 0x70
	s_addc_u32 s38, s67, 0
	v_bitop3_b32 v10, v2, v3, 48 bitop3:0x6c
	v_and_b32_e32 v11, 64, v1
	v_and_or_b32 v6, v5, s4, v12
	s_movk_i32 s4, 0x60
	v_add_u32_e32 v14, 0x2000, v2
	s_add_u32 s39, s66, 0xdc00000
	v_or_b32_e32 v3, v10, v11
	v_and_or_b32 v5, v5, s4, v4
	v_lshrrev_b32_e32 v2, 7, v14
	s_movk_i32 s4, 0xf0
	s_addc_u32 s40, s67, 0
	v_lshl_or_b32 v132, v5, 11, v3
	v_and_or_b32 v5, v2, s4, v12
	s_movk_i32 s4, 0xe0
	s_ashr_i32 s42, s2, 31
	v_and_or_b32 v2, v2, s4, v4
	s_lshr_b32 s4, s42, 29
	s_add_i32 s4, s2, s4
	s_lshr_b32 s12, s5, 6
	s_ashr_i32 s8, s4, 3
	s_and_b32 s4, s4, -8
	s_lshr_b32 s14, s5, 8
	s_lshl_b32 s41, s12, 10
	s_sub_i32 s4, s2, s4
	s_cmp_lt_i32 s4, 0
	s_movk_i32 s43, 0xb1
	s_cselect_b32 s9, s43, 0xb0
	s_mul_i32 s4, s4, s9
	s_add_i32 s4, s4, s8
	s_mul_hi_i32 s8, s4, 0x2e8ba2e9
	s_lshr_b32 s9, s8, 31
	s_ashr_i32 s8, s8, 4
	s_add_i32 s8, s8, s9
	s_lshl_b32 s9, s8, 2
	s_mulk_i32 s8, 0x58
	s_sub_i32 s8, s4, s8
	s_bfe_i32 s4, s8, 0x80000
	s_bfe_u32 s4, s4, 0x2000d
	s_add_i32 s10, s8, s4
	s_bfe_i32 s4, s10, 0x80000
	s_and_b32 s10, s10, 0xfc
	s_sub_i32 s8, s8, s10
	s_sext_i32_i8 s8, s8
	s_add_i32 s24, s9, s8
	s_sext_i32_i16 s4, s4
	s_ashr_i32 s25, s24, 31
	s_lshr_b32 s4, s4, 2
	s_lshl_b64 s[8:9], s[24:25], 19
	s_add_u32 s30, s33, s8
	s_addc_u32 s31, s38, s9
	s_bfe_i64 s[8:9], s[4:5], 0x100000
	s_lshl_b64 s[8:9], s[8:9], 18
	s_add_u32 s34, s39, s8
	s_addc_u32 s35, s40, s9
	s_add_i32 s25, s41, 0
	s_add_i32 m0, s25, 0x10000
	v_lshl_or_b32 v136, v2, 11, v3
	global_load_lds_dwordx4 v132, s[34:35]
	s_add_i32 m0, s25, 0x12000
	s_add_u32 s8, s34, 0x580000
	global_load_lds_dwordx4 v136, s[34:35]
	s_addc_u32 s9, s35, 0
	s_add_i32 m0, s25, 0x14000
	s_add_i32 s46, s25, 0x2000
	global_load_lds_dwordx4 v132, s[8:9]
	s_add_i32 m0, s25, 0x16000
	v_lshl_or_b32 v130, v6, 11, v3
	global_load_lds_dwordx4 v136, s[8:9]
	s_mov_b32 m0, s25
	s_add_u32 s8, s30, 0x40000
	v_lshl_or_b32 v134, v5, 11, v3
	global_load_lds_dwordx4 v130, s[30:31]
	s_mov_b32 m0, s46
	s_addc_u32 s9, s31, 0
	s_add_i32 s47, s25, 0x4000
	global_load_lds_dwordx4 v134, s[30:31]
	s_mov_b32 m0, s47
	s_add_i32 s48, s25, 0x6000
	global_load_lds_dwordx4 v130, s[8:9]
	s_mov_b32 m0, s48
	v_mov_b32_e32 v133, 0
	global_load_lds_dwordx4 v134, s[8:9]
	v_mov_b32_e32 v137, v133
	v_mov_b32_e32 v131, v133
	v_mov_b32_e32 v135, v133
	s_cmp_eq_u32 s14, 1
	s_mov_b32 s49, 0
	v_lshl_add_u64 v[8:9], s[34:35], 0, v[132:133]
	v_lshl_add_u64 v[6:7], s[34:35], 0, v[136:137]
	v_lshl_add_u64 v[2:3], s[30:31], 0, v[130:131]
	s_cselect_b64 s[8:9], -1, 0
	s_cmp_lg_u32 s14, 1
	v_lshl_add_u64 v[4:5], s[30:31], 0, v[134:135]
	s_cbranch_scc1 .LBB0_1443
	s_barrier

.LBB0_1456:
.LBB0_1459:
	s_cmp_gt_i32 s69, 13
	s_cselect_b64 s[4:5], -1, 0
	s_and_b64 s[6:7], s[6:7], s[4:5]
	s_andn2_b64 vcc, exec, s[6:7]
	s_cbranch_vccnz .LBB0_1527
	s_cmpk_lt_u32 s69, 0x3e9
	s_mov_b64 s[6:7], -1
	s_cbranch_scc0 .LBB0_1514
	s_waitcnt vmcnt(0)
	s_waitcnt vmcnt(0)
	s_barrier
	s_mov_b64 s[6:7], exec
	v_readlane_b32 s8, v240, 4
	v_readlane_b32 s9, v240, 5
	s_and_b64 s[8:9], s[6:7], s[8:9]
	s_mov_b64 exec, s[8:9]
	s_cbranch_execz .LBB0_1513
	s_add_i32 s8, 0, 0x26000
	v_mov_b32_e32 v2, s8
	s_waitcnt vmcnt(0) expcnt(0) lgkmcnt(0)
	ds_read_b32 v4, v2
	s_add_i32 s8, 0, 0x26004
	v_mov_b32_e32 v2, s8
	ds_read_b32 v2, v2
	s_waitcnt lgkmcnt(1)
	v_cmp_ne_u32_e32 vcc, 0, v4
	s_cbranch_vccnz .LBB0_1477
	s_load_dword s8, s[0:1], 0x110
	s_mov_b32 s44, 1
	v_mov_b32_e32 v18, 0
	s_waitcnt lgkmcnt(0)
	s_mul_i32 s33, s71, s8
	s_add_u32 s8, s66, 0x1bc0200
	s_addc_u32 s9, s67, 0
	s_add_u32 s10, s66, 0x1bc0400
	s_addc_u32 s11, s67, 0
	s_add_u32 s12, s66, 0x1bc0500
	s_addc_u32 s13, s67, 0
	s_add_u32 s14, s66, 0x1bc0600
	s_addc_u32 s15, s67, 0
	s_add_u32 s16, s66, 0x1bc0700
	s_addc_u32 s17, s67, 0
	s_add_u32 s18, s66, 0x1bc0800
	s_addc_u32 s19, s67, 0
	s_add_u32 s20, s66, 0x1bc0900
	s_addc_u32 s21, s67, 0
	s_add_u32 s22, s66, 0x1bc0a00
	s_addc_u32 s23, s67, 0
	s_add_u32 s24, s66, 0x1bc0b00
	s_addc_u32 s25, s67, 0
	s_add_u32 s26, s66, 0x1bc0c00
	s_addc_u32 s27, s67, 0
	s_add_u32 s28, s66, 0x1bc0d00
	s_addc_u32 s29, s67, 0
	s_add_u32 s30, s66, 0x1bc0e00
	s_addc_u32 s31, s67, 0
	s_add_u32 s34, s66, 0x1bc0f00
	s_addc_u32 s35, s67, 0
	s_add_u32 s36, s66, 0x1bc1000
	s_addc_u32 s37, s67, 0
	s_add_u32 s38, s66, 0x1bc1100
	s_addc_u32 s39, s67, 0
	s_add_u32 s40, s66, 0x1bc1200
	s_addc_u32 s41, s67, 0
	s_add_u32 s42, s66, 0x1bc1300
	s_mul_i32 s33, s33, s70
	s_addc_u32 s43, s67, 0
	s_branch .LBB0_1465
